# attention: second unit's Q and q-aug loads issued together with the first unit's prologue loads into spare VGPRs, first K/V/aug tiles kept in registers; the second unit's prologue no longer waits on m
# speedup vs baseline: 1.0146x; 1.0013x over previous
; #define LAS __attribute__((address_space(3)))
; __device__ __forceinline__ void attn_unit(const Params& p, LAS unsigned char* lds, int bh, int qb, float mshift, int tid, int lane, int wave) {
;     ...
;     const int q_rel = 32 * wave + r32, tq = 256 * qb + q_rel;
;     bf16x8 qr[4], qa;
;     { const bf16_t* qp = Qg + ((size_t)(b * S_ + tq)) * 512 + h * 64 + 8 * hi;
; #pragma unroll
;       for (int d0 = 0; d0 < 4; ++d0) qr[d0] = *(const bf16x8*)(qp + 16 * d0);
;       u32x4 t = qaug[tq]; if (hi) t = (u32x4){0u, 0u, 0u, 0u}; qa = __builtin_bit_cast(bf16x8, t); }
;     f32x16 o[2]; float lsum = 0.f;
; #pragma unroll
;     for (int i = 0; i < 16; ++i) { o[0][i] = 0.f; o[1][i] = 0.f; }
;     const int NT = 4 * (qb + 1);
;     const int srow = tid >> 3, sch = tid & 7;
;     const bf16_t* kp = Kg + ((size_t)(b * S_ + srow)) * 512 + h * 64 + 8 * sch;
;     const bf16_t* vp = Vg + ((size_t)(bh * 64 + srow)) * S_ + 8 * sch;
;     u32x4 kreg = *(const u32x4*)kp, vreg = *(const u32x4*)vp, areg = (u32x4){0u, 0u, 0u, 0u};
;     if (tid < 64) areg = kaug[tid];
;     { LAS unsigned char* bb = lds; *(LAS u32x4*)(bb + AB_K + srow * 144 + sch * 16) = kreg; *(LAS u32x4*)(bb + AB_V + srow * 144 + sch * 16) = vreg; if (tid < 64) *(LAS u32x4*)(bb + AB_A + tid * 16) = areg; }
;     __syncthreads();
; __device__ __forceinline__ void phase3(const Params& p, LAS unsigned char* lds, int tid, int lane, int wave) {
;     ...
;         for (int rep = 0; rep < 2; ++rep) { int e = rep; asm volatile("" : "+s"(e)); attn_unit(p, lds, bh, e ? s : 7 - s, mshift, tid, lane, wave); }
.LBB0_354:
	s_cmp_eq_u32 s16, 0
	s_cselect_b32 s38, s44, s43
	s_cbranch_scc0 .Lat_u2
	s_lshl_b32 s16, s38, 8
	v_add_u32_e32 v64, s16, v175
	v_add_u32_e32 v16, s45, v64
	v_ashrrev_i32_e32 v17, 31, v16
	v_lshlrev_b64 v[16:17], 10, v[16:17]
	v_lshl_add_u64 v[16:17], v[154:155], 0, v[16:17]
	global_load_dwordx4 v[80:83], v[16:17], off
	global_load_dwordx4 v[76:79], v[16:17], off offset:32
	global_load_dwordx4 v[72:75], v[16:17], off offset:64
	global_load_dwordx4 v[68:71], v[16:17], off offset:96
	v_lshl_add_u64 v[28:29], v[64:65], 4, s[34:35]
	global_load_dwordx4 v[16:19], v[28:29], off
	global_load_dwordx4 v[20:23], v[156:157], off
	global_load_dwordx4 v[24:27], v[158:159], off
	v_mov_b32_e32 v66, v65
	v_mov_b32_e32 v67, v65
	v_mov_b32_e32 v64, v65
	v_mov_b64_e32 v[90:91], v[66:67]
	v_mov_b64_e32 v[88:89], v[64:65]
	s_and_saveexec_b64 s[36:37], s[8:9]
	s_cbranch_execz .LBB0_356
	global_load_dwordx4 v[88:91], v[160:161], off
.LBB0_356:
	s_or_b64 exec, exec, s[36:37]
	s_lshl_b32 s1, s43, 8
	v_add_u32_e32 v210, s1, v175
	v_add_u32_e32 v212, s45, v210
	v_ashrrev_i32_e32 v213, 31, v212
	v_lshlrev_b64 v[212:213], 10, v[212:213]
	v_lshl_add_u64 v[212:213], v[154:155], 0, v[212:213]
	global_load_dwordx4 v[214:217], v[212:213], off
	global_load_dwordx4 v[218:221], v[212:213], off offset:32
	global_load_dwordx4 v[222:225], v[212:213], off offset:64
	global_load_dwordx4 v[226:229], v[212:213], off offset:96
	v_mov_b32_e32 v211, v65
	v_lshl_add_u64 v[246:247], v[210:211], 4, s[34:35]
	global_load_dwordx4 v[230:233], v[246:247], off
	s_waitcnt vmcnt(6)
	v_mov_b32_e32 v234, v20
	v_mov_b32_e32 v235, v21
	v_mov_b32_e32 v236, v22
	v_mov_b32_e32 v237, v23
	s_waitcnt vmcnt(5)
	v_mov_b32_e32 v238, v24
	v_mov_b32_e32 v239, v25
	v_mov_b32_e32 v240, v26
	v_mov_b32_e32 v241, v27
	v_mov_b32_e32 v242, v88
	v_mov_b32_e32 v243, v89
	v_mov_b32_e32 v244, v90
	v_mov_b32_e32 v245, v91
	s_branch .Lat_join
.Lat_u2:
	s_lshl_b32 s16, s38, 8
	v_mov_b32_e32 v80, v214
	v_mov_b32_e32 v81, v215
	v_mov_b32_e32 v82, v216
	v_mov_b32_e32 v83, v217
	v_mov_b32_e32 v76, v218
	v_mov_b32_e32 v77, v219
	v_mov_b32_e32 v78, v220
	v_mov_b32_e32 v79, v221
	v_mov_b32_e32 v72, v222
	v_mov_b32_e32 v73, v223
	v_mov_b32_e32 v74, v224
	v_mov_b32_e32 v75, v225
	v_mov_b32_e32 v68, v226
	v_mov_b32_e32 v69, v227
	v_mov_b32_e32 v70, v228
	v_mov_b32_e32 v71, v229
	v_mov_b32_e32 v16, v230
	v_mov_b32_e32 v17, v231
	v_mov_b32_e32 v18, v232
	v_mov_b32_e32 v19, v233
	v_mov_b32_e32 v20, v234
	v_mov_b32_e32 v21, v235
	v_mov_b32_e32 v22, v236
	v_mov_b32_e32 v23, v237
	v_mov_b32_e32 v24, v238
	v_mov_b32_e32 v25, v239
	v_mov_b32_e32 v26, v240
	v_mov_b32_e32 v27, v241
	v_mov_b32_e32 v88, v242
	v_mov_b32_e32 v89, v243
	v_mov_b32_e32 v90, v244
	v_mov_b32_e32 v91, v245
	v_mov_b32_e32 v66, v65
	v_mov_b32_e32 v67, v65
	v_mov_b32_e32 v64, v65
.Lat_join:
	ds_write_b128 v101, v[20:23]
	ds_write_b128 v101, v[24:27] offset:9216
	s_and_saveexec_b64 s[36:37], s[8:9]
	v_add_u32_e32 v20, 0, v102
	ds_write_b128 v20, v[88:91] offset:18432
	s_or_b64 exec, exec, s[36:37]
	s_lshl_b32 s48, s38, 2
	v_mov_b32_e32 v64, 0
	s_xor_b64 s[36:37], s[10:11], -1
	v_cndmask_b32_e64 v87, 0, v19, s[6:7]
	v_cndmask_b32_e64 v86, 0, v18, s[6:7]
	v_cndmask_b32_e64 v85, 0, v17, s[6:7]
	v_cndmask_b32_e64 v84, 0, v16, s[6:7]
	s_mov_b32 s47, 0
	s_sub_i32 s49, 0, s16
	s_sub_i32 s50, 0, s48
	v_mov_b64_e32 v[66:67], v[168:169]
	v_mov_b64_e32 v[170:171], v[166:167]
	v_mov_b64_e32 v[172:173], v[164:165]
	v_mov_b32_e32 v16, 0
	v_mov_b32_e32 v17, v64
	v_mov_b32_e32 v18, v64
	v_mov_b32_e32 v19, v64
	v_mov_b32_e32 v20, v64
	v_mov_b32_e32 v21, v64
	v_mov_b32_e32 v22, v64
	v_mov_b32_e32 v23, v64
	v_mov_b32_e32 v24, v64
	v_mov_b32_e32 v25, v64
	v_mov_b32_e32 v26, v64
	v_mov_b32_e32 v27, v64
	v_mov_b32_e32 v28, v64
	v_mov_b32_e32 v29, v64
	v_mov_b32_e32 v30, v64
	v_mov_b32_e32 v31, v64
	v_mov_b32_e32 v32, v64
	v_mov_b32_e32 v33, v64
	v_mov_b32_e32 v34, v64
	v_mov_b32_e32 v35, v64
	v_mov_b32_e32 v36, v64
	v_mov_b32_e32 v37, v64
	v_mov_b32_e32 v38, v64
	v_mov_b32_e32 v39, v64
	v_mov_b32_e32 v40, v64
	v_mov_b32_e32 v41, v64
	v_mov_b32_e32 v42, v64
	v_mov_b32_e32 v43, v64
	v_mov_b32_e32 v44, v64
	v_mov_b32_e32 v45, v64
	v_mov_b32_e32 v46, v64
	v_mov_b32_e32 v47, v64
	s_waitcnt lgkmcnt(0)
	s_barrier
	s_branch .LBB0_360
